# speedup vs baseline: 1.0023x; 1.0000x over previous
; DEVI void partialSM(f32x16& p0, f32x16& p1, float& m_reg, float& mn, float& alpha) {
;     ...
;   for (int r = 0; r < 16; ++r) p0[r] = fmaf(p0[r], C, mnC);
; #pragma unroll
;   for (int r = 0; r < 16; ++r) p1[r] = fmaf(p1[r], C, mnC);
; #pragma unroll
;   for (int r = 0; r < 16; ++r) p0[r] = __builtin_amdgcn_exp2f(p0[r]);
; }
; DEVI void finishSM(f32x16& p0, f32x16& p1, float alpha, float& l_reg, bf16x8& pa0, bf16x8& pa1, bf16x8& pa2, bf16x8& pa3) {
; #pragma unroll
;   for (int r = 0; r < 16; ++r) p1[r] = __builtin_amdgcn_exp2f(p1[r]);
;   float ps = 0;
; #pragma unroll
;   for (int r = 0; r < 16; ++r) ps += p0[r];
; #pragma unroll
;   for (int r = 0; r < 16; ++r) ps += p1[r];
;   { auto rr = __builtin_amdgcn_permlane32_swap(__float_as_uint(ps), __float_as_uint(ps), false, false);
;     ps = __uint_as_float(rr[0]) + __uint_as_float(rr[1]); }
;   l_reg = l_reg * alpha + ps;
;     ...
;   PK4(p0, 0, pa0); PK4(p0, 8, pa1); PK4(p1, 0, pa2); PK4(p1, 8, pa3);
; DEVI void qkt(f32x16& p0, f32x16& p1, const char* Ks, const char* Rs, const bf16x8* qr, const char* Qrs, int r32, int hi) {
;   p0 = f32x16{}; p1 = f32x16{};
; #pragma unroll
;   for (int d0 = 0; d0 < 8; ++d0) { int cb = (d0 * 16 + hi * 8) * 2;
;     bf16x8 b0 = *reinterpret_cast<const bf16x8*>(Ks + KSWZ(r32, cb));
;     bf16x8 b1 = *reinterpret_cast<const bf16x8*>(Ks + KSWZ(32 + r32, cb));
;     p0 = __builtin_amdgcn_mfma_f32_32x32x16_bf16(b0, qr[d0], p0, 0, 0, 0);
;     p1 = __builtin_amdgcn_mfma_f32_32x32x16_bf16(b1, qr[d0], p1, 0, 0, 0); }
.LBB0_985:
	v_cndmask_b32_e64 v222, v140, v222, s[8:9]
	v_mul_f32_e32 v152, 0xbdd53b94, v222
	v_fmamk_f32 v66, v66, 0x3dd53b94, v152
	v_fmamk_f32 v67, v67, 0x3dd53b94, v152
	v_exp_f32_e32 v141, v66
	v_add_u32_e32 v66, 0x40000, v168
	v_fmamk_f32 v68, v68, 0x3dd53b94, v152
	v_exp_f32_e32 v236, v67
	v_fmamk_f32 v69, v69, 0x3dd53b94, v152
	v_exp_f32_e32 v237, v68
	v_add_u32_e32 v68, 0x60000, v168
	v_fmamk_f32 v128, v64, 0x3dd53b94, v152
	v_exp_f32_e32 v238, v69
	v_exp_f32_e32 v140, v128
	s_waitcnt lgkmcnt(0)
	s_barrier
	global_load_dwordx4 v[128:131], v66, s[36:37] offset:3072
	v_add_u32_e32 v66, 0x2000, v166
	global_load_dwordx4 v[132:135], v68, s[36:37] offset:3072
	global_load_dwordx4 v[136:139], v66, s[36:37] offset:3072
	v_fmamk_f32 v74, v74, 0x3dd53b94, v152
	v_fmamk_f32 v75, v75, 0x3dd53b94, v152
	v_exp_f32_e32 v228, v74
	v_exp_f32_e32 v229, v75
	v_fmamk_f32 v65, v65, 0x3dd53b94, v152
	v_fmamk_f32 v70, v70, 0x3dd53b94, v152
	v_fmamk_f32 v71, v71, 0x3dd53b94, v152
	v_fmamk_f32 v72, v72, 0x3dd53b94, v152
	v_fmamk_f32 v73, v73, 0x3dd53b94, v152
	v_fmamk_f32 v76, v76, 0x3dd53b94, v152
	v_fmamk_f32 v77, v77, 0x3dd53b94, v152
	v_fmamk_f32 v78, v78, 0x3dd53b94, v152
	v_fmamk_f32 v79, v79, 0x3dd53b94, v152
	v_fmamk_f32 v64, v80, 0x3dd53b94, v152
	v_fmamk_f32 v80, v81, 0x3dd53b94, v152
	v_fmamk_f32 v241, v82, 0x3dd53b94, v152
	v_fmamk_f32 v145, v83, 0x3dd53b94, v152
	v_fmamk_f32 v144, v84, 0x3dd53b94, v152
	v_fmamk_f32 v143, v85, 0x3dd53b94, v152
	v_fmamk_f32 v142, v86, 0x3dd53b94, v152
	v_fmamk_f32 v239, v87, 0x3dd53b94, v152
	v_fmamk_f32 v154, v88, 0x3dd53b94, v152
	v_fmamk_f32 v150, v89, 0x3dd53b94, v152
	v_fmamk_f32 v146, v90, 0x3dd53b94, v152
	v_fmamk_f32 v147, v91, 0x3dd53b94, v152
	v_fmamk_f32 v148, v92, 0x3dd53b94, v152
	v_exp_f32_e32 v240, v65
	v_exp_f32_e32 v234, v70
	v_exp_f32_e32 v235, v71
	v_exp_f32_e32 v232, v72
	v_exp_f32_e32 v233, v73
	v_exp_f32_e32 v230, v76
	v_exp_f32_e32 v231, v77
	v_exp_f32_e32 v153, v78
	v_exp_f32_e32 v155, v79
	v_fmamk_f32 v149, v93, 0x3dd53b94, v152
	v_fmamk_f32 v151, v94, 0x3dd53b94, v152
	v_fmac_f32_e32 v152, 0x3dd53b94, v95
	ds_read_b128 v[66:69], v187 offset:32768
	v_add_f32_e32 v65, 0, v140
	v_add_f32_e32 v65, v240, v65
	v_add_f32_e32 v81, v141, v65
	v_exp_f32_e32 v209, v64
	s_cmp_eq_u32 s4, s2
	s_cselect_b64 vcc, -1, 0
	s_waitcnt lgkmcnt(0)
	v_mfma_f32_32x32x16_bf16 v[64:79], v[66:69], v[96:99], 0
	ds_read_b128 v[82:85], v187 offset:40960
	v_add_f32_e32 v81, v236, v81
	v_add_f32_e32 v81, v237, v81
	v_add_f32_e32 v210, v238, v81
	v_exp_f32_e32 v211, v80
	s_waitcnt lgkmcnt(0)
	v_mfma_f32_32x32x16_bf16 v[80:95], v[82:85], v[96:99], 0
	ds_read_b128 v[170:173], v188 offset:32768
	v_add_f32_e32 v210, v234, v210
	v_add_f32_e32 v210, v235, v210
	v_add_f32_e32 v210, v232, v210
	v_exp_f32_e32 v212, v241
	s_waitcnt lgkmcnt(0)
	v_mfma_f32_32x32x16_bf16 v[64:79], v[170:173], v[100:103], v[64:79]
	ds_read_b128 v[170:173], v188 offset:40960
	v_add_f32_e32 v210, v233, v210
	v_add_f32_e32 v210, v228, v210
	v_add_f32_e32 v210, v229, v210
	v_exp_f32_e32 v214, v145
	s_waitcnt lgkmcnt(0)
	v_mfma_f32_32x32x16_bf16 v[80:95], v[170:173], v[100:103], v[80:95]
	ds_read_b128 v[170:173], v189 offset:32768
	v_add_f32_e32 v145, v230, v210
	v_add_f32_e32 v145, v231, v145
	v_add_f32_e32 v145, v153, v145
	v_exp_f32_e32 v210, v144
	s_waitcnt lgkmcnt(0)
	v_mfma_f32_32x32x16_bf16 v[64:79], v[170:173], v[104:107], v[64:79]
	ds_read_b128 v[170:173], v189 offset:40960
	v_add_f32_e32 v144, v155, v145
	v_add_f32_e32 v144, v209, v144
	v_add_f32_e32 v144, v211, v144
	v_exp_f32_e32 v215, v143
	s_waitcnt lgkmcnt(0)
	v_mfma_f32_32x32x16_bf16 v[80:95], v[170:173], v[104:107], v[80:95]
	ds_read_b128 v[170:173], v190 offset:32768
	v_add_f32_e32 v143, v212, v144
	v_add_f32_e32 v143, v214, v143
	v_add_f32_e32 v216, v210, v143
	v_exp_f32_e32 v217, v142
	s_waitcnt lgkmcnt(0)
	v_mfma_f32_32x32x16_bf16 v[64:79], v[170:173], v[108:111], v[64:79]
	ds_read_b128 v[142:145], v190 offset:40960
	v_add_f32_e32 v170, v215, v216
	v_cvt_pk_bf16_f32 v140, v140, v240
	v_add_f32_e32 v216, v217, v170
	v_exp_f32_e32 v218, v239
	s_waitcnt lgkmcnt(0)
	v_mfma_f32_32x32x16_bf16 v[80:95], v[142:145], v[108:111], v[80:95]
	ds_read_b128 v[170:173], v191 offset:32768
	v_cvt_pk_bf16_f32 v141, v141, v236
	v_cvt_pk_bf16_f32 v142, v237, v238
	v_add_f32_e32 v143, v218, v216
	v_exp_f32_e32 v154, v154
	s_waitcnt lgkmcnt(0)
	v_mfma_f32_32x32x16_bf16 v[64:79], v[170:173], v[112:115], v[64:79]
	ds_read_b128 v[170:173], v191 offset:40960
	v_add_f32_e32 v144, v154, v143
	v_cvt_pk_bf16_f32 v143, v234, v235
	v_permlane32_swap_b32_e32 v140, v142
	v_exp_f32_e32 v216, v150
	s_waitcnt lgkmcnt(0)
	v_mfma_f32_32x32x16_bf16 v[80:95], v[170:173], v[112:115], v[80:95]
	ds_read_b128 v[170:173], v192 offset:32768
	v_add_f32_e32 v145, v216, v144
	v_permlane32_swap_b32_e32 v141, v143
	v_cvt_pk_bf16_f32 v144, v232, v233
	v_exp_f32_e32 v219, v146
	s_waitcnt lgkmcnt(0)
	v_mfma_f32_32x32x16_bf16 v[64:79], v[170:173], v[116:119], v[64:79]
	ds_read_b128 v[170:173], v192 offset:40960
	v_add_f32_e32 v150, v219, v145
	v_cvt_pk_bf16_f32 v145, v228, v229
	v_cvt_pk_bf16_f32 v146, v230, v231
	v_exp_f32_e32 v236, v147
	s_waitcnt lgkmcnt(0)
	v_mfma_f32_32x32x16_bf16 v[80:95], v[170:173], v[116:119], v[80:95]
	ds_read_b128 v[170:173], v193 offset:32768
	v_add_f32_e32 v150, v236, v150
	v_cvt_pk_bf16_f32 v147, v153, v155
	v_permlane32_swap_b32_e32 v144, v146
	v_exp_f32_e32 v155, v148
	s_waitcnt lgkmcnt(0)
	v_mfma_f32_32x32x16_bf16 v[64:79], v[170:173], v[120:123], v[64:79]
	ds_read_b128 v[170:173], v193 offset:40960
	v_add_f32_e32 v150, v155, v150
	v_permlane32_swap_b32_e32 v145, v147
	v_cvt_pk_bf16_f32 v148, v209, v211
	v_exp_f32_e32 v209, v149
	s_waitcnt lgkmcnt(0)
; #define SBAR() __builtin_amdgcn_sched_barrier(0)
; #define SGB_QK() _Pragma("unroll") for (int g_ = 0; g_ < 24; ++g_) { __builtin_amdgcn_sched_group_barrier(0x008, 1, 0); __builtin_amdgcn_sched_group_barrier(0x100, 1, 0); \
;     __builtin_amdgcn_sched_group_barrier(0x002, 3, 0); __builtin_amdgcn_sched_group_barrier(0x400, 1, 0); }
; #define SLOAD_V(k0) do { const char* vb_ = (const char*)VTh + (size_t)(k0) * 2; const char* vb2_ = vb_ + vhalf;                \
;     vs0 = *reinterpret_cast<const bf16x8*>(vb_ + vo_v); vs1 = *reinterpret_cast<const bf16x8*>(vb2_ + vo_v); } while (0)
; DEVI void partialSM(f32x16& p0, f32x16& p1, float& m_reg, float& mn, float& alpha) {
;     ...
;   float pmax = p0[0];
; #pragma unroll
;   for (int r = 1; r < 16; ++r) pmax = fmaxf(pmax, p0[r]);
; #pragma unroll
;   for (int r = 0; r < 16; ++r) pmax = fmaxf(pmax, p1[r]);
;   { auto rr = __builtin_amdgcn_permlane32_swap(__float_as_uint(pmax), __float_as_uint(pmax), false, false);
;     pmax = fmaxf(__uint_as_float(rr[0]), __uint_as_float(rr[1])); }
;   if (__builtin_expect(__all(pmax - m_reg <= ATHR / ASCALE), 1)) { mn = m_reg; alpha = 1.f; }
;   else { mn = fmaxf(m_reg, pmax); alpha = __builtin_amdgcn_exp2f((m_reg - mn) * C); m_reg = mn; }
;   float mnC = -mn * C;
; #pragma unroll
;   for (int r = 0; r < 16; ++r) p0[r] = fmaf(p0[r], C, mnC);
; DEVI void attn_item(const u16* __restrict__ Qb, const u16* __restrict__ KNh, const u16* __restrict__ VTh, int Lpad, const u16* __restrict__ KRb,
;                     const u16* __restrict__ SZb, u16* __restrict__ AOb, int NT, char* lds, const int wid_s_) {
;     ...
;     if (j + 1 == NT - 2) mask_tile(pA0, pA1, true);
;     finishSM(pB0, pB1, alB, l_reg, pa0, pa1, pa2, pa3); SGB_QK(); SBAR();
;     SLOAD_V((j + 2) * 64); SBAR();
;     pv_d0(o, V_lds + SHM_V, r32, hi, pa0, pa1, pa2, pa3); partialSM(pA0, pA1, m_reg, mnA, alA);
	v_mfma_f32_32x32x16_bf16 v[80:95], v[170:173], v[120:123], v[80:95]
	ds_read_b128 v[170:173], v194 offset:32768
	v_add_f32_e32 v153, v209, v150
	v_cvt_pk_bf16_f32 v149, v212, v214
	v_cvt_pk_bf16_f32 v150, v210, v215
	v_exp_f32_e32 v210, v151
	s_waitcnt lgkmcnt(0)
	v_mfma_f32_32x32x16_bf16 v[64:79], v[170:173], v[124:127], v[64:79]
	ds_read_b128 v[170:173], v194 offset:40960
	v_add_f32_e32 v153, v210, v153
	v_cvt_pk_bf16_f32 v151, v217, v218
	v_permlane32_swap_b32_e32 v148, v150
	v_exp_f32_e32 v211, v152
	s_waitcnt lgkmcnt(0)
	v_mfma_f32_32x32x16_bf16 v[80:95], v[170:173], v[124:127], v[80:95]
	ds_read_b128 v[228:231], v195
	v_add_f32_e32 v170, v211, v153
	v_mov_b32_e32 v171, v170
	v_permlane32_swap_b32_e32 v149, v151
	ds_read_b128 v[232:235], v195 offset:4096
	v_permlane32_swap_b32_e32 v170, v171
	v_cvt_pk_bf16_f32 v152, v154, v216
	v_cvt_pk_bf16_f32 v153, v219, v236
	ds_read_b128 v[236:239], v196
	s_waitcnt lgkmcnt(0)
	v_mfma_f32_32x32x16_bf16 v[64:79], v[228:231], v[236:239], v[64:79]
	ds_read_b128 v[228:231], v197
	v_mfma_f32_32x32x16_bf16 v[80:95], v[232:235], v[236:239], v[80:95]
	ds_read_b128 v[240:243], v198
	ds_read_b128 v[232:235], v202
	ds_read_b128 v[236:239], v199 offset:4096
	s_waitcnt lgkmcnt(2)
	v_mfma_f32_32x32x16_bf16 v[64:79], v[228:231], v[240:243], v[64:79]
	ds_read_b128 v[228:231], v199
	ds_read_b128 v[244:247], v200
	s_waitcnt lgkmcnt(0)
	v_mfma_f32_32x32x16_bf16 v[64:79], v[228:231], v[244:247], v[64:79]
	ds_read_b128 v[228:231], v201
	s_waitcnt lgkmcnt(0)
	v_mfma_f32_32x32x16_bf16 v[64:79], v[228:231], v[232:235], v[64:79]
	ds_read_b128 v[226:229], v197 offset:4096
	s_waitcnt lgkmcnt(0)
	v_mfma_f32_32x32x16_bf16 v[80:95], v[226:229], v[240:243], v[80:95]
	ds_read_b128 v[240:243], v201 offset:4096
	v_cvt_pk_bf16_f32 v154, v155, v209
	v_cvt_pk_bf16_f32 v155, v210, v211
	s_nop 0
	v_permlane32_swap_b32_e32 v152, v154
	v_permlane32_swap_b32_e32 v153, v155
	v_mfma_f32_32x32x16_bf16 v[80:95], v[236:239], v[244:247], v[80:95]
	s_nop 1
	v_cndmask_b32_e32 v229, v72, v208, vcc
	v_cndmask_b32_e32 v227, v76, v208, vcc
	v_cndmask_b32_e32 v228, v73, v208, vcc
	s_waitcnt lgkmcnt(0)
	v_mfma_f32_32x32x16_bf16 v[80:95], v[240:243], v[232:235], v[80:95]
	s_nop 11
	v_cndmask_b32_e32 v73, v95, v208, vcc
	v_cndmask_b32_e32 v226, v74, v208, vcc
	v_cndmask_b32_e32 v172, v79, v208, vcc
	v_cndmask_b32_e32 v173, v78, v208, vcc
	v_cndmask_b32_e32 v223, v77, v208, vcc
	v_cndmask_b32_e32 v225, v75, v208, vcc
	v_cndmask_b32_e32 v72, v94, v208, vcc
	v_cndmask_b32_e32 v75, v93, v208, vcc
	v_cndmask_b32_e32 v74, v92, v208, vcc
	v_cndmask_b32_e32 v77, v91, v208, vcc
	v_cndmask_b32_e32 v76, v90, v208, vcc
	v_cndmask_b32_e32 v79, v89, v208, vcc
	v_cndmask_b32_e32 v78, v88, v208, vcc
	v_cndmask_b32_e32 v87, v87, v208, vcc
	v_cndmask_b32_e32 v86, v86, v208, vcc
	v_cndmask_b32_e32 v85, v85, v208, vcc
	v_cndmask_b32_e32 v84, v84, v208, vcc
	v_cndmask_b32_e32 v83, v83, v208, vcc
	v_cndmask_b32_e32 v82, v82, v208, vcc
	v_cndmask_b32_e32 v81, v81, v208, vcc
	v_cndmask_b32_e32 v80, v80, v208, vcc
	global_load_dwordx4 v[90:93], v162, s[36:37] offset:3456
	global_load_dwordx4 v[156:159], v164, s[36:37] offset:3456
	ds_read_b128 v[230:233], v177 offset:16384
	ds_read_b128 v[234:237], v161 offset:16384
	ds_read_b128 v[238:241], v180 offset:16384
	v_max_f32_e32 v88, v65, v65
	v_max_f32_e32 v89, v64, v64
	s_waitcnt lgkmcnt(2)
	v_mfma_f32_32x32x16_bf16 v[16:31], v[140:143], v[230:233], v[16:31]
	ds_read_b128 v[230:233], v177 offset:20480
	v_max_f32_e32 v88, v89, v88
	v_max3_f32 v88, v88, v66, v67
	v_max3_f32 v88, v88, v68, v69
	ds_read_b128 v[242:245], v179 offset:16384
	v_max3_f32 v88, v88, v70, v71
	v_max3_f32 v88, v88, v229, v228
	s_waitcnt lgkmcnt(1)
	v_mfma_f32_32x32x16_bf16 v[48:63], v[140:143], v[230:233], v[48:63]
	ds_read_b128 v[230:233], v177 offset:24576
	v_max3_f32 v88, v88, v226, v225
	v_max3_f32 v88, v88, v227, v223
	v_max3_f32 v88, v88, v173, v172
	v_max3_f32 v88, v88, v80, v81
	v_max3_f32 v88, v88, v82, v83
	v_max3_f32 v88, v88, v84, v85
	v_mfma_f32_32x32x16_bf16 v[16:31], v[144:147], v[234:237], v[16:31]
	ds_read_b128 v[234:237], v161 offset:20480
	v_max3_f32 v88, v88, v86, v87
	v_max3_f32 v88, v88, v78, v79
	v_max3_f32 v88, v88, v76, v77
	v_max3_f32 v88, v88, v74, v75
	v_max3_f32 v88, v88, v72, v73
	v_mov_b32_e32 v89, v88
	s_waitcnt lgkmcnt(1)
	v_mfma_f32_32x32x16_bf16 v[32:47], v[140:143], v[230:233], v[32:47]
	ds_read_b128 v[230:233], v177 offset:28672
	v_permlane32_swap_b32_e32 v88, v89
	v_max_f32_e32 v89, v89, v89
	v_max_f32_e32 v88, v88, v88
	v_max_f32_e32 v88, v88, v89
	v_sub_f32_e32 v89, v88, v222
	s_waitcnt lgkmcnt(1)
	v_mfma_f32_32x32x16_bf16 v[48:63], v[144:147], v[234:237], v[48:63]
	ds_read_b128 v[234:237], v161 offset:24576
	v_cmp_ge_f32_e32 vcc, s91, v89
	v_max_f32_e32 v89, v222, v222
	v_max_f32_e32 v89, v89, v88
	v_sub_f32_e32 v88, v222, v89
	v_mul_f32_e32 v88, 0x3dd53b94, v88
	v_exp_f32_e32 v88, v88
	s_waitcnt lgkmcnt(1)
	v_mfma_f32_32x32x16_bf16 v[0:15], v[140:143], v[230:233], v[0:15]
	s_cmp_eq_u64 vcc, exec
	s_cselect_b64 s[8:9], -1, 0
	v_cndmask_b32_e64 v88, v88, 1.0, s[8:9]
	v_cmp_gt_f32_e32 vcc, 1.0, v88
	v_cndmask_b32_e64 v167, v89, v222, s[8:9]
	v_mul_f32_e32 v167, 0xbdd53b94, v167
	v_mfma_f32_32x32x16_bf16 v[16:31], v[148:151], v[238:241], v[16:31]
	ds_read_b128 v[238:241], v180 offset:20480
	v_fmamk_f32 v64, v64, 0x3dd53b94, v167
	v_fmamk_f32 v65, v65, 0x3dd53b94, v167
	s_waitcnt lgkmcnt(1)
; #define SWRITE_KR(b) do { int kc = sc * 2; *(bf16x8*)(K_lds + (b) * SHM_K + KSWZ(sr, kc)) = ks0; *(bf16x8*)(K_lds + (b) * SHM_K + KSWZ(32 + sr, kc)) = ks1; \
;     *(bf16x8*)(R_lds + (b) * SHM_R + RSWZ(rr_, rc_ * 2)) = rs0; } while (0)
; #define SWRITE_V(b) do { *(bf16x8*)(V_lds + (b) * SHM_V + RSWZ(vd, vc * 16)) = vs0; *(bf16x8*)(V_lds + (b) * SHM_V + RSWZ(vd + 64, vc * 16)) = vs1; } while (0)
; #define SWAIT() asm volatile("s_waitcnt vmcnt(0)" ::: "memory")
; #define RESC(a) do { if (__any((a) < 1.f)) { if (hi == 0) al_l[r32] = (a); asm volatile("s_waitcnt lgkmcnt(0)" ::: "memory"); \
;     _Pragma("unroll") for (int d = 0; d < 4; ++d) _Pragma("unroll") for (int r = 0; r < 16; ++r) o[d][r] *= al_l[crow(r, hi)]; } } while (0)
; DEVI void partialSM(f32x16& p0, f32x16& p1, float& m_reg, float& mn, float& alpha) {
;     ...
;   float mnC = -mn * C;
; #pragma unroll
;   for (int r = 0; r < 16; ++r) p0[r] = fmaf(p0[r], C, mnC);
; #pragma unroll
;   for (int r = 0; r < 16; ++r) p1[r] = fmaf(p1[r], C, mnC);
; #pragma unroll
;   for (int r = 0; r < 16; ++r) p0[r] = __builtin_amdgcn_exp2f(p0[r]);
; DEVI void attn_item(const u16* __restrict__ Qb, const u16* __restrict__ KNh, const u16* __restrict__ VTh, int Lpad, const u16* __restrict__ KRb,
;                     const u16* __restrict__ SZb, u16* __restrict__ AOb, int NT, char* lds, const int wid_s_) {
;     ...
;     pv_d0(o, V_lds + SHM_V, r32, hi, pa0, pa1, pa2, pa3); partialSM(pA0, pA1, m_reg, mnA, alA);
;     SWRITE_KR(1);
;     __syncthreads(); SWAIT(); SWRITE_V(1);
;     RESC(alA); __syncthreads();
;   }
	v_mfma_f32_32x32x16_bf16 v[32:47], v[144:147], v[234:237], v[32:47]
	ds_read_b128 v[234:237], v161 offset:28672
	v_fmamk_f32 v66, v66, 0x3dd53b94, v167
	v_fmamk_f32 v67, v67, 0x3dd53b94, v167
	s_waitcnt lgkmcnt(1)
	v_mfma_f32_32x32x16_bf16 v[48:63], v[148:151], v[238:241], v[48:63]
	ds_read_b128 v[238:241], v180 offset:24576
	v_fmamk_f32 v68, v68, 0x3dd53b94, v167
	v_fmamk_f32 v69, v69, 0x3dd53b94, v167
	s_waitcnt lgkmcnt(1)
	v_mfma_f32_32x32x16_bf16 v[0:15], v[144:147], v[234:237], v[0:15]
	v_mfma_f32_32x32x16_bf16 v[16:31], v[152:155], v[242:245], v[16:31]
	ds_read_b128 v[242:245], v179 offset:20480
	v_fmamk_f32 v70, v70, 0x3dd53b94, v167
	v_fmamk_f32 v71, v71, 0x3dd53b94, v167
	s_waitcnt lgkmcnt(1)
	v_mfma_f32_32x32x16_bf16 v[32:47], v[148:151], v[238:241], v[32:47]
	ds_read_b128 v[238:241], v180 offset:28672
	v_fmamk_f32 v229, v229, 0x3dd53b94, v167
	v_fmamk_f32 v228, v228, 0x3dd53b94, v167
	s_waitcnt lgkmcnt(1)
	v_mfma_f32_32x32x16_bf16 v[48:63], v[152:155], v[242:245], v[48:63]
	ds_read_b128 v[242:245], v179 offset:24576
	v_fmamk_f32 v226, v226, 0x3dd53b94, v167
	v_fmamk_f32 v225, v225, 0x3dd53b94, v167
	s_waitcnt lgkmcnt(1)
	v_mfma_f32_32x32x16_bf16 v[0:15], v[148:151], v[238:241], v[0:15]
	v_fmamk_f32 v227, v227, 0x3dd53b94, v167
	v_fmamk_f32 v223, v223, 0x3dd53b94, v167
	s_waitcnt lgkmcnt(0)
	v_mfma_f32_32x32x16_bf16 v[32:47], v[152:155], v[242:245], v[32:47]
	ds_read_b128 v[242:245], v179 offset:28672
	v_fmamk_f32 v173, v173, 0x3dd53b94, v167
	v_fmamk_f32 v172, v172, 0x3dd53b94, v167
	s_waitcnt vmcnt(2)
	ds_write_b128 v184, v[128:131] offset:49152
	ds_write_b128 v184, v[132:135] offset:57344
	ds_write_b128 v203, v[136:139]
	s_waitcnt lgkmcnt(0)
	s_barrier
	v_mfma_f32_32x32x16_bf16 v[0:15], v[152:155], v[242:245], v[0:15]
	s_waitcnt vmcnt(0)
	ds_write_b128 v185, v[90:93] offset:16384
	ds_write_b128 v185, v[156:159] offset:24576
	s_cbranch_vccz .LBB0_989
	s_and_saveexec_b64 s[14:15], s[6:7]
	ds_write_b32 v181, v88 offset:128
	s_or_b64 exec, exec, s[14:15]
	s_waitcnt lgkmcnt(0)
	v_add_u32_e32 v94, v178, v160
	ds_read_b128 v[90:93], v94 offset:224
	ds_read_b128 v[128:131], v94 offset:192
	ds_read_b128 v[132:135], v94 offset:160
	ds_read_b128 v[136:139], v94 offset:128
	s_waitcnt lgkmcnt(3)
	v_pk_mul_f32 v[28:29], v[28:29], v[90:91]
	s_waitcnt lgkmcnt(2)
	v_pk_mul_f32 v[24:25], v[24:25], v[128:129]
	s_waitcnt lgkmcnt(1)
	v_pk_mul_f32 v[20:21], v[20:21], v[132:133]
	v_pk_mul_f32 v[30:31], v[30:31], v[92:93]
	v_pk_mul_f32 v[26:27], v[26:27], v[130:131]
	v_pk_mul_f32 v[22:23], v[22:23], v[134:135]
	s_waitcnt lgkmcnt(0)
	v_pk_mul_f32 v[18:19], v[18:19], v[138:139]
	v_pk_mul_f32 v[16:17], v[16:17], v[136:137]
	v_pk_mul_f32 v[60:61], v[60:61], v[90:91]
	v_pk_mul_f32 v[56:57], v[56:57], v[128:129]
	v_pk_mul_f32 v[52:53], v[52:53], v[132:133]
	v_pk_mul_f32 v[62:63], v[62:63], v[92:93]
	v_pk_mul_f32 v[58:59], v[58:59], v[130:131]
	v_pk_mul_f32 v[54:55], v[54:55], v[134:135]
	v_pk_mul_f32 v[50:51], v[50:51], v[138:139]
	v_pk_mul_f32 v[48:49], v[48:49], v[136:137]
	v_pk_mul_f32 v[44:45], v[44:45], v[90:91]
	v_pk_mul_f32 v[40:41], v[40:41], v[128:129]
	v_pk_mul_f32 v[36:37], v[36:37], v[132:133]
	v_pk_mul_f32 v[46:47], v[46:47], v[92:93]
	v_pk_mul_f32 v[42:43], v[42:43], v[130:131]
	v_pk_mul_f32 v[38:39], v[38:39], v[134:135]
	v_pk_mul_f32 v[34:35], v[34:35], v[138:139]
	v_pk_mul_f32 v[32:33], v[32:33], v[136:137]
	v_pk_mul_f32 v[12:13], v[12:13], v[90:91]
	v_pk_mul_f32 v[8:9], v[8:9], v[128:129]
	v_pk_mul_f32 v[4:5], v[4:5], v[132:133]
	v_pk_mul_f32 v[14:15], v[14:15], v[92:93]
	v_pk_mul_f32 v[10:11], v[10:11], v[130:131]
	v_pk_mul_f32 v[6:7], v[6:7], v[134:135]
	v_pk_mul_f32 v[2:3], v[2:3], v[138:139]
	v_pk_mul_f32 v[0:1], v[0:1], v[136:137]
.LBB0_989:
	v_cndmask_b32_e64 v222, v89, v222, s[8:9]
	v_mul_f32_e32 v90, 0xbdd53b94, v222
	v_exp_f32_e32 v231, v64
	v_exp_f32_e32 v235, v65
	v_exp_f32_e32 v230, v66
	v_exp_f32_e32 v232, v67
	v_exp_f32_e32 v233, v68
	v_exp_f32_e32 v236, v69
	v_exp_f32_e32 v234, v70
	v_exp_f32_e32 v237, v71
	v_exp_f32_e32 v156, v229
	v_exp_f32_e32 v157, v228
	v_exp_f32_e32 v158, v226
	v_exp_f32_e32 v159, v225
	v_exp_f32_e32 v228, v227
	v_exp_f32_e32 v229, v223
	v_exp_f32_e32 v154, v173
	v_exp_f32_e32 v155, v172
	v_add_f32_e32 v64, v204, v221
	v_fmac_f32_e32 v64, v220, v182
	v_add_f32_e32 v182, v170, v171
	v_add_u32_e32 v166, 0x4000, v166
	s_add_i32 s1, s2, 2
	v_pk_fma_f32 v[80:81], v[80:81], s[80:81], v[90:91] op_sel_hi:[1,0,0]
	v_pk_fma_f32 v[152:153], v[82:83], s[80:81], v[90:91] op_sel_hi:[1,0,0]
	v_pk_fma_f32 v[150:151], v[84:85], s[80:81], v[90:91] op_sel_hi:[1,0,0]
	v_pk_fma_f32 v[148:149], v[86:87], s[80:81], v[90:91] op_sel_hi:[1,0,0]
	v_pk_fma_f32 v[142:143], v[78:79], s[80:81], v[90:91] op_sel_hi:[1,0,0]
	v_pk_fma_f32 v[146:147], v[76:77], s[80:81], v[90:91] op_sel_hi:[1,0,0]
	v_pk_fma_f32 v[140:141], v[74:75], s[80:81], v[90:91] op_sel_hi:[1,0,0]
	v_pk_fma_f32 v[144:145], v[72:73], s[80:81], v[90:91] op_sel_hi:[1,0,0]
	v_fmac_f32_e32 v182, v64, v224
	v_add_u32_e32 v162, s82, v162
	v_add_u32_e32 v164, s82, v164
	s_cmp_ge_u32 s2, s4
	v_add_u32_e32 v168, 0x80000, v168
	s_waitcnt lgkmcnt(0)
	s_barrier
	s_cbranch_scc1 .LBB0_991
	s_mov_b32 s2, s1
	v_mov_b32_e32 v220, v88
	s_branch .LBB0_981
